# grid barrier: all workgroups spin on the top-level arrival counter reaching (gen+1)*nx; the separate generation word is no longer on the critical path
# speedup vs baseline: 1.0046x; 1.0046x over previous
; DI unsigned xb_ld(unsigned* p) { return __hip_atomic_load(p, __ATOMIC_RELAXED, __HIP_MEMORY_SCOPE_AGENT); }
; DI unsigned xb_add(unsigned* p, unsigned v) { return __hip_atomic_fetch_add(p, v, __ATOMIC_RELAXED, __HIP_MEMORY_SCOPE_AGENT); }
; #define XB_SPIN(cond, bar) do { unsigned _sp = 0; while (cond) { __builtin_amdgcn_s_sleep(1); \
;     if ((++_sp & 255u) == 0u) { if (xb_ld(&(bar)[XB_TMO])) break; if (_sp > XB_SPIN_CAP) { atomicAdd(&(bar)[XB_TMO], 1u); break; } } } } while (0)
; DI void xcd_barrier(unsigned* bar, const unsigned x, volatile LAS unsigned* st, const int tid) {
;     ...
;     const unsigned old = xb_add(&bar[XB_XSUB(x)], 1u);
;     const unsigned gen = old / nloc;
;     if (old + 1u == (gen + 1u) * nloc) {
;       __builtin_amdgcn_fence(__ATOMIC_RELEASE, "agent");
;       asm volatile("s_waitcnt vmcnt(0)" ::: "memory");
;       const unsigned og = xb_add(&bar[XB_TOP], 1u);
;       const unsigned tg = og / nx;
;       if (og + 1u == (tg + 1u) * nx) xb_add(&bar[XB_TOPGEN], 1u);
;       else XB_SPIN(xb_ld(&bar[XB_TOPGEN]) == tg, bar);
;       __builtin_amdgcn_fence(__ATOMIC_ACQUIRE, "agent");
;       xb_add(&bar[XB_XGEN(x)], 1u);
;       asm volatile("s_waitcnt vmcnt(0)" ::: "memory");
;     } else {
;       XB_SPIN(xb_ld(&bar[XB_XGEN(x)]) == gen, bar);
.LBB0_1279:
	s_or_b64 exec, exec, s[2:3]
	v_cvt_f32_u32_e32 v5, v3
	s_waitcnt vmcnt(0)
	v_readfirstlane_b32 s2, v4
	v_sub_u32_e32 v4, 0, v3
	v_rcp_iflag_f32_e32 v5, v5
	v_add_u32_e32 v6, s2, v0
	v_mul_f32_e32 v5, 0x4f7ffffe, v5
	v_cvt_u32_f32_e32 v5, v5
	v_mul_lo_u32 v0, v4, v5
	v_mul_hi_u32 v0, v5, v0
	v_add_u32_e32 v0, v5, v0
	v_mul_hi_u32 v0, v6, v0
	v_mul_lo_u32 v4, v0, v3
	v_sub_u32_e32 v4, v6, v4
	v_add_u32_e32 v5, 1, v0
	v_cmp_ge_u32_e32 vcc, v4, v3
	s_nop 1
	v_cndmask_b32_e32 v0, v0, v5, vcc
	v_sub_u32_e32 v5, v4, v3
	v_cndmask_b32_e32 v4, v4, v5, vcc
	v_add_u32_e32 v5, 1, v0
	v_cmp_ge_u32_e32 vcc, v4, v3
	v_add_u32_e32 v4, 1, v6
	s_nop 0
	v_cndmask_b32_e32 v0, v0, v5, vcc
	v_mul_lo_u32 v5, v3, v0
	v_add_u32_e32 v3, v5, v3
	v_cmp_ne_u32_e32 vcc, v4, v3
	s_and_saveexec_b64 s[2:3], vcc
	s_xor_b64 s[2:3], exec, s[2:3]
	s_cbranch_execz .LBB0_1293
	v_readlane_b32 s4, v252, 56
	v_readlane_b32 s5, v252, 57
	s_waitcnt lgkmcnt(0)
	v_add_u32_e32 v0, 1, v0
	v_mul_lo_u32 v0, v0, v2
	s_nop 3
	global_load_dword v2, v1, s[4:5] sc1
	s_waitcnt vmcnt(0)
	v_cmp_lt_u32_e32 vcc, v2, v0
	s_and_saveexec_b64 s[4:5], vcc
	s_cbranch_execz .LBB0_1292
	s_mov_b32 s16, 1
	s_mov_b64 s[6:7], 0
	s_branch .LBB0_1283

.LBB0_1285:
	v_readlane_b32 s10, v252, 56
	v_readlane_b32 s11, v252, 57
	s_add_i32 s16, s16, 1
	s_mov_b64 s[12:13], -1
	s_nop 2
	global_load_dword v2, v1, s[10:11] sc1
	s_waitcnt vmcnt(0)
	v_cmp_ge_u32_e32 vcc, v2, v0
	s_orn2_b64 s[10:11], vcc, exec
	s_branch .LBB0_1282

; DI unsigned xb_ld(unsigned* p) { return __hip_atomic_load(p, __ATOMIC_RELAXED, __HIP_MEMORY_SCOPE_AGENT); }
; DI unsigned xb_add(unsigned* p, unsigned v) { return __hip_atomic_fetch_add(p, v, __ATOMIC_RELAXED, __HIP_MEMORY_SCOPE_AGENT); }
; #define XB_SPIN(cond, bar) do { unsigned _sp = 0; while (cond) { __builtin_amdgcn_s_sleep(1); \
;     if ((++_sp & 255u) == 0u) { if (xb_ld(&(bar)[XB_TMO])) break; if (_sp > XB_SPIN_CAP) { atomicAdd(&(bar)[XB_TMO], 1u); break; } } } } while (0)
; DI void xcd_barrier(unsigned* bar, const unsigned x, volatile LAS unsigned* st, const int tid) {
;     ...
;       const unsigned og = xb_add(&bar[XB_TOP], 1u);
;       const unsigned tg = og / nx;
;       if (og + 1u == (tg + 1u) * nx) xb_add(&bar[XB_TOPGEN], 1u);
;       else XB_SPIN(xb_ld(&bar[XB_TOPGEN]) == tg, bar);
.LBB0_1296:
	s_or_b64 exec, exec, s[4:5]
	s_waitcnt vmcnt(0)
	v_readfirstlane_b32 s2, v3
	v_sub_u32_e32 v4, 0, v2
	s_mov_b64 s[4:5], -1
	v_add_u32_e32 v3, s2, v0
	v_cvt_f32_u32_e32 v0, v2
	v_readlane_b32 s2, v252, 58
	v_readlane_b32 s3, v252, 59
	v_rcp_iflag_f32_e32 v0, v0
	s_nop 0
	v_mul_f32_e32 v0, 0x4f7ffffe, v0
	v_cvt_u32_f32_e32 v0, v0
	v_mul_lo_u32 v4, v4, v0
	v_mul_hi_u32 v4, v0, v4
	v_add_u32_e32 v0, v0, v4
	v_mul_hi_u32 v0, v3, v0
	v_mul_lo_u32 v4, v0, v2
	v_sub_u32_e32 v4, v3, v4
	v_cmp_ge_u32_e32 vcc, v4, v2
	v_add_u32_e32 v5, 1, v0
	v_add_u32_e32 v3, 1, v3
	v_cndmask_b32_e32 v0, v0, v5, vcc
	v_sub_u32_e32 v5, v4, v2
	v_cndmask_b32_e32 v4, v4, v5, vcc
	v_cmp_ge_u32_e32 vcc, v4, v2
	v_add_u32_e32 v4, 1, v0
	s_nop 0
	v_cndmask_b32_e32 v0, v0, v4, vcc
	v_mul_lo_u32 v4, v2, v0
	v_add_u32_e32 v2, v4, v2
	v_cmp_ne_u32_e32 vcc, v3, v2
	v_mov_b32_e32 v5, v2
	v_mov_b64_e32 v[2:3], s[2:3]
	s_and_saveexec_b64 s[2:3], vcc
	s_cbranch_execz .LBB0_1308
	v_readlane_b32 s4, v252, 56
	v_readlane_b32 s5, v252, 57
	s_mov_b64 s[6:7], 0
	s_nop 3
	global_load_dword v2, v1, s[4:5] sc1
	s_waitcnt vmcnt(0)
	v_cmp_lt_u32_e32 vcc, v2, v5
	s_and_saveexec_b64 s[4:5], vcc
	s_cbranch_execz .LBB0_1307
	s_mov_b32 s16, 1
	s_branch .LBB0_1300

.LBB0_1302:
	v_readlane_b32 s10, v252, 56
	v_readlane_b32 s11, v252, 57
	s_add_i32 s16, s16, 1
	s_mov_b64 s[12:13], -1
	s_nop 2
	global_load_dword v2, v1, s[10:11] sc1
	s_waitcnt vmcnt(0)
	v_cmp_ge_u32_e32 vcc, v2, v5
	s_orn2_b64 s[10:11], vcc, exec
	s_branch .LBB0_1299
